# GEMM loop: per-block s_setprio flips removed, static s_setprio 1 for waves 0-3 (the other half, A/B against the waves 4-7 form)
# baseline (speedup 1.0000x reference)
; __device__ __forceinline__ void gemm_phase(LAS unsigned char* lds, const Params& p, const Sched& S, float alpha, const int TIDX) {
;     ...
;     for (;;) {
;         const bool has_next = S.next(ui + 1, nxt);
;         const char* nA = has_next ? nxt.a : cA; const char* nB = has_next ? nxt.b : cB;
;         for (int t = 0; t < nt; t += 2) {
.LBB0_287:
	s_cmp_lt_i32 s79, 1
	s_cbranch_scc1 .LBB0_290
	s_add_i32 s38, s79, -2
	s_add_u32 s6, s58, 0x80
	s_addc_u32 s7, s59, 0
	s_add_u32 s39, s60, 0x100
	s_addc_u32 s56, s61, 0
	s_mov_b32 s48, 0
	v_readlane_b32 s74, v254, 3
	s_nop 3
	s_cmp_ge_u32 s74, 4
	s_cbranch_scc1 .Lgemm_prio_done
	s_setprio 1
